# LN1+LN2 phases: MFMA A/B swapped + hand-written LayerNorm epilogue (no LDS staging, wide loads/stores, permlane row stats)
# speedup vs baseline: 1.0226x; 1.0038x over previous
.LBB0_413:
	s_mul_hi_u32 s27, s23, 0xaaaaaaab
	s_lshr_b32 s27, s27, 1
	s_mul_i32 s27, s27, 0x24000
	s_waitcnt lgkmcnt(0)
	v_mfma_f32_16x16x32_bf16 v[66:69], v[22:25], v[26:29], v[66:69]
	v_add_u32_e32 v222, s14, v113
	s_mul_hi_u32 s34, s19, 0xaaaaaaab
	s_lshr_b32 s34, s34, 1
	v_mfma_f32_16x16x32_bf16 v[62:65], v[18:21], v[26:29], v[62:65]
	s_mul_i32 s34, s34, 0x24000
	v_subrev_u32_e32 v182, s34, v126
	v_subrev_u32_e32 v191, s34, v127
	v_mfma_f32_16x16x32_bf16 v[58:61], v[10:13], v[26:29], v[58:61]
	v_subrev_u32_e32 v201, s34, v128
	v_mfma_f32_16x16x32_bf16 v[54:57], v[6:9], v[26:29], v[54:57]
	v_subrev_u32_e32 v26, s27, v125
	v_mfma_f32_16x16x32_bf16 v[50:53], v[22:25], v[14:17], v[50:53]
	v_mfma_f32_16x16x32_bf16 v[46:49], v[18:21], v[14:17], v[46:49]
	v_mfma_f32_16x16x32_bf16 v[42:45], v[10:13], v[14:17], v[42:45]
	v_mfma_f32_16x16x32_bf16 v[38:41], v[6:9], v[14:17], v[38:41]
	v_subrev_u32_e32 v14, s27, v129
	v_add_u32_e32 v16, v222, v26
	v_add_u32_e32 v14, v222, v14
	v_mfma_f32_16x16x32_bf16 v[34:37], v[22:25], v[30:33], v[34:37]
	v_subrev_u32_e32 v15, s34, v130
	v_mfma_f32_16x16x32_bf16 v[86:89], v[22:25], v[2:5], v[86:89]
	ds_read_b128 v[22:25], v16
	ds_read_b128 v[174:177], v16 offset:2048
	ds_read_b128 v[178:181], v16 offset:4096
	ds_read_b128 v[202:205], v16 offset:6144
	ds_read_b128 v[206:209], v14 offset:32768
	ds_read_b128 v[210:213], v14 offset:34816
	ds_read_b128 v[214:217], v14 offset:36864
	ds_read_b128 v[218:221], v14 offset:38912
	v_mfma_f32_16x16x32_bf16 v[74:77], v[18:21], v[30:33], v[74:77]
	v_mfma_f32_16x16x32_bf16 v[70:73], v[10:13], v[30:33], v[70:73]
	v_mfma_f32_16x16x32_bf16 v[78:81], v[6:9], v[30:33], v[78:81]
	v_mfma_f32_16x16x32_bf16 v[94:97], v[18:21], v[2:5], v[94:97]
	v_mfma_f32_16x16x32_bf16 v[90:93], v[10:13], v[2:5], v[90:93]
	v_mfma_f32_16x16x32_bf16 v[82:85], v[6:9], v[2:5], v[82:85]
	s_add_i32 s27, s13, 4
	s_mul_i32 s34, s27, 0xab
	s_bfe_u32 s34, s34, 0x70009
	s_mul_i32 s34, s34, 3
	s_sub_i32 s27, s27, s34
	s_and_b32 s27, s27, 0xff
	s_mul_i32 s27, s27, 0xc000
	s_waitcnt vmcnt(6)
	v_add_u32_e32 v2, v222, v15
	v_add_u32_e32 v6, v222, v201
	s_waitcnt lgkmcnt(0)
	v_mfma_f32_16x16x32_bf16 v[66:69], v[206:209], v[174:177], v[66:69]
	s_mov_b64 s[36:37], 0xe1d8180
	s_add_i32 s34, s27, s8
	s_waitcnt lgkmcnt(0)
	v_mfma_f32_16x16x32_bf16 v[62:65], v[210:213], v[174:177], v[62:65]
	s_barrier
	ds_read_b128 v[30:33], v2
	ds_read_b128 v[26:29], v2 offset:2048
	ds_read_b128 v[14:17], v2 offset:4096
	ds_read_b128 v[2:5], v2 offset:6144
	v_mfma_f32_16x16x32_bf16 v[58:61], v[214:217], v[174:177], v[58:61]
	v_add_u32_e32 v7, v222, v191
	s_mov_b32 m0, s34
	s_add_i32 s27, s27, s9
	v_mfma_f32_16x16x32_bf16 v[54:57], v[218:221], v[174:177], v[54:57]
	v_lshl_add_u64 v[174:175], v[108:109], 0, v[98:99]
	v_lshl_add_u64 v[176:177], v[174:175], 0, s[36:37]
	s_mov_b64 s[36:37], 0xe1e8180
	v_mfma_f32_16x16x32_bf16 v[34:37], v[206:209], v[22:25], v[34:37]
	s_add_i32 s23, s23, 1
	v_mfma_f32_16x16x32_bf16 v[74:77], v[210:213], v[22:25], v[74:77]
	v_mfma_f32_16x16x32_bf16 v[70:73], v[214:217], v[22:25], v[70:73]
	v_mfma_f32_16x16x32_bf16 v[78:81], v[218:221], v[22:25], v[78:81]
	ds_read_b128 v[22:25], v6
	ds_read_b128 v[18:21], v7
	v_add_u32_e32 v6, v222, v182
	ds_read_b128 v[10:13], v6
	ds_read_b128 v[6:9], v6 offset:2048
	global_load_lds_dwordx4 v[176:177], off
	v_lshl_add_u64 v[176:177], v[174:175], 0, s[36:37]
	s_add_i32 m0, s34, 0x400
	s_mov_b64 s[36:37], 0xe1f8180
	global_load_lds_dwordx4 v[176:177], off
	v_lshl_add_u64 v[176:177], v[174:175], 0, s[36:37]
	s_add_i32 m0, s34, 0x800
	s_mov_b64 s[36:37], 0xe208180
	global_load_lds_dwordx4 v[176:177], off
	v_lshl_add_u64 v[174:175], v[174:175], 0, s[36:37]
	s_add_i32 m0, s34, 0xc00
	s_mov_b64 s[36:37], 0x4300180
	global_load_lds_dwordx4 v[174:175], off
	v_lshl_add_u64 v[174:175], v[110:111], 0, v[98:99]
	v_lshl_add_u64 v[176:177], v[174:175], 0, s[36:37]
	s_add_i32 m0, s27, 0x8000
	s_mov_b64 s[36:37], 0x4310180
	global_load_lds_dwordx4 v[176:177], off
	v_lshl_add_u64 v[174:175], v[174:175], 0, s[36:37]
	s_add_i32 m0, s27, 0x8400
	v_mfma_f32_16x16x32_bf16 v[50:53], v[206:209], v[178:181], v[50:53]
	global_load_lds_dwordx4 v[174:175], off
	v_mfma_f32_16x16x32_bf16 v[46:49], v[210:213], v[178:181], v[46:49]
	v_mfma_f32_16x16x32_bf16 v[42:45], v[214:217], v[178:181], v[42:45]
	v_mfma_f32_16x16x32_bf16 v[38:41], v[218:221], v[178:181], v[38:41]
	v_mfma_f32_16x16x32_bf16 v[86:89], v[206:209], v[202:205], v[86:89]
	v_mfma_f32_16x16x32_bf16 v[94:97], v[210:213], v[202:205], v[94:97]
	v_mfma_f32_16x16x32_bf16 v[90:93], v[214:217], v[202:205], v[90:93]
	v_mfma_f32_16x16x32_bf16 v[82:85], v[218:221], v[202:205], v[82:85]
	s_add_i32 s13, s13, 1
	s_add_i32 s14, s14, 0xc000
	s_add_i32 s19, s19, 1
	v_lshl_add_u64 v[108:109], v[108:109], 0, s[2:3]
	s_cmp_eq_u32 s14, 0x2dc000
	v_lshl_add_u64 v[110:111], v[110:111], 0, s[2:3]
	s_cbranch_scc0 .LBB0_413
	s_waitcnt lgkmcnt(0)
	v_mfma_f32_16x16x32_bf16 v[34:37], v[22:25], v[30:33], v[34:37]
	v_mfma_f32_16x16x32_bf16 v[74:77], v[18:21], v[30:33], v[74:77]
	v_mfma_f32_16x16x32_bf16 v[70:73], v[10:13], v[30:33], v[70:73]
	v_mfma_f32_16x16x32_bf16 v[30:33], v[6:9], v[30:33], v[78:81]
	v_mfma_f32_16x16x32_bf16 v[66:69], v[22:25], v[26:29], v[66:69]
	v_mfma_f32_16x16x32_bf16 v[62:65], v[18:21], v[26:29], v[62:65]
	v_mfma_f32_16x16x32_bf16 v[58:61], v[10:13], v[26:29], v[58:61]
	v_mfma_f32_16x16x32_bf16 v[26:29], v[6:9], v[26:29], v[54:57]
	v_mfma_f32_16x16x32_bf16 v[50:53], v[22:25], v[14:17], v[50:53]
	v_mfma_f32_16x16x32_bf16 v[46:49], v[18:21], v[14:17], v[46:49]
	v_mfma_f32_16x16x32_bf16 v[42:45], v[10:13], v[14:17], v[42:45]
	v_mfma_f32_16x16x32_bf16 v[14:17], v[6:9], v[14:17], v[38:41]
	v_mfma_f32_16x16x32_bf16 v[22:25], v[22:25], v[2:5], v[86:89]
	s_nop 1
	ds_read_b128 v[38:41], v131
	ds_read_b128 v[54:57], v132 offset:2048
	ds_read_b128 v[78:81], v132 offset:4096
	ds_read_b128 v[86:89], v132 offset:6144
	v_mfma_f32_16x16x32_bf16 v[18:21], v[18:21], v[2:5], v[94:97]
	v_mfma_f32_16x16x32_bf16 v[10:13], v[10:13], v[2:5], v[90:93]
	s_nop 2
	ds_read_b128 v[90:93], v133 offset:32768
	ds_read_b128 v[94:97], v134 offset:34816
	ds_read_b128 v[108:111], v134 offset:36864
	ds_read_b128 v[174:177], v134 offset:38912
	v_mfma_f32_16x16x32_bf16 v[2:5], v[6:9], v[2:5], v[82:85]
	s_waitcnt lgkmcnt(0)
	v_mfma_f32_16x16x32_bf16 v[6:9], v[90:93], v[38:41], v[34:37]
	s_waitcnt vmcnt(6)
	s_waitcnt lgkmcnt(0)
	s_barrier
	v_mfma_f32_16x16x32_bf16 v[34:37], v[94:97], v[38:41], v[74:77]
	v_mfma_f32_16x16x32_bf16 v[70:73], v[108:111], v[38:41], v[70:73]
	v_mfma_f32_16x16x32_bf16 v[30:33], v[174:177], v[38:41], v[30:33]
	v_mfma_f32_16x16x32_bf16 v[38:41], v[90:93], v[54:57], v[66:69]
	v_mfma_f32_16x16x32_bf16 v[62:65], v[94:97], v[54:57], v[62:65]
	v_mfma_f32_16x16x32_bf16 v[58:61], v[108:111], v[54:57], v[58:61]
	v_mfma_f32_16x16x32_bf16 v[26:29], v[174:177], v[54:57], v[26:29]
	v_add_u32_e32 v54, v124, v115
	ds_read_b128 v[54:57], v54
	ds_read_b128 v[66:69], v135 offset:2048
	v_mfma_f32_16x16x32_bf16 v[50:53], v[90:93], v[78:81], v[50:53]
	v_mfma_f32_16x16x32_bf16 v[46:49], v[94:97], v[78:81], v[46:49]
	v_mfma_f32_16x16x32_bf16 v[42:45], v[108:111], v[78:81], v[42:45]
	v_mfma_f32_16x16x32_bf16 v[22:25], v[90:93], v[86:89], v[22:25]
	v_add_u32_e32 v90, 0x20800, v164
	v_mfma_f32_16x16x32_bf16 v[18:21], v[94:97], v[86:89], v[18:21]
	v_add_u32_e32 v94, 0x21000, v164
	v_mfma_f32_16x16x32_bf16 v[10:13], v[108:111], v[86:89], v[10:13]
	v_add_u32_e32 v108, 0x21800, v164
	v_mfma_f32_16x16x32_bf16 v[14:17], v[174:177], v[78:81], v[14:17]
	ds_read_b128 v[74:77], v135 offset:4096
	ds_read_b128 v[78:81], v135 offset:6144
	ds_read_b128 v[82:85], v163
	ds_read_b128 v[90:93], v90
	ds_read_b128 v[94:97], v94
	ds_read_b128 v[108:111], v108
	v_mfma_f32_16x16x32_bf16 v[2:5], v[174:177], v[86:89], v[2:5]
	s_waitcnt lgkmcnt(0)
	v_mfma_f32_16x16x32_bf16 v[6:9], v[82:85], v[54:57], v[6:9]
	v_mfma_f32_16x16x32_bf16 v[34:37], v[90:93], v[54:57], v[34:37]
	v_mfma_f32_16x16x32_bf16 v[70:73], v[94:97], v[54:57], v[70:73]
	v_mfma_f32_16x16x32_bf16 v[30:33], v[108:111], v[54:57], v[30:33]
	v_mfma_f32_16x16x32_bf16 v[54:57], v[90:93], v[66:69], v[62:65]
	s_nop 2
	v_add_u32_e32 v62, v124, v119
	v_mfma_f32_16x16x32_bf16 v[38:41], v[82:85], v[66:69], v[38:41]
	v_mfma_f32_16x16x32_bf16 v[58:61], v[94:97], v[66:69], v[58:61]
	v_mfma_f32_16x16x32_bf16 v[26:29], v[108:111], v[66:69], v[26:29]
	v_mfma_f32_16x16x32_bf16 v[50:53], v[82:85], v[74:77], v[50:53]
	v_mfma_f32_16x16x32_bf16 v[46:49], v[90:93], v[74:77], v[46:49]
	v_mfma_f32_16x16x32_bf16 v[42:45], v[94:97], v[74:77], v[42:45]
	v_mfma_f32_16x16x32_bf16 v[14:17], v[108:111], v[74:77], v[14:17]
	v_mfma_f32_16x16x32_bf16 v[22:25], v[82:85], v[78:81], v[22:25]
	ds_read_b128 v[62:65], v62
	ds_read_b128 v[66:69], v165
	ds_read_b128 v[74:77], v166
	ds_read_b128 v[82:85], v167
	v_mfma_f32_16x16x32_bf16 v[18:21], v[90:93], v[78:81], v[18:21]
	v_mfma_f32_16x16x32_bf16 v[10:13], v[94:97], v[78:81], v[10:13]
	ds_read_b128 v[86:89], v168
	ds_read_b128 v[90:93], v169
	ds_read_b128 v[94:97], v170
	ds_read_b128 v[174:177], v171
	v_mfma_f32_16x16x32_bf16 v[2:5], v[108:111], v[78:81], v[2:5]
	s_waitcnt vmcnt(0)
	s_waitcnt lgkmcnt(0)
	v_mfma_f32_16x16x32_bf16 v[6:9], v[86:89], v[62:65], v[6:9]
	s_waitcnt lgkmcnt(0)
	s_barrier
	v_mfma_f32_16x16x32_bf16 v[34:37], v[90:93], v[62:65], v[34:37]
	v_mfma_f32_16x16x32_bf16 v[70:73], v[94:97], v[62:65], v[70:73]
	v_mfma_f32_16x16x32_bf16 v[30:33], v[174:177], v[62:65], v[30:33]
	v_mfma_f32_16x16x32_bf16 v[38:41], v[86:89], v[66:69], v[38:41]
	v_mfma_f32_16x16x32_bf16 v[54:57], v[90:93], v[66:69], v[54:57]
	v_mfma_f32_16x16x32_bf16 v[58:61], v[94:97], v[66:69], v[58:61]
	v_mfma_f32_16x16x32_bf16 v[26:29], v[174:177], v[66:69], v[26:29]
	v_mfma_f32_16x16x32_bf16 v[50:53], v[86:89], v[74:77], v[50:53]
	v_mfma_f32_16x16x32_bf16 v[46:49], v[90:93], v[74:77], v[46:49]
	v_mfma_f32_16x16x32_bf16 v[42:45], v[94:97], v[74:77], v[42:45]
	v_mfma_f32_16x16x32_bf16 v[14:17], v[174:177], v[74:77], v[14:17]
	ds_read_b128 v[62:65], v164 offset:38912
	ds_read_b128 v[66:69], v164 offset:36864
	ds_read_b128 v[74:77], v164 offset:34816
	ds_read_b128 v[78:81], v161 offset:32768
	v_mfma_f32_16x16x32_bf16 v[22:25], v[86:89], v[82:85], v[22:25]
	v_mfma_f32_16x16x32_bf16 v[18:21], v[90:93], v[82:85], v[18:21]
	v_mfma_f32_16x16x32_bf16 v[10:13], v[94:97], v[82:85], v[10:13]
	ds_read_b128 v[86:89], v173 offset:6144
	ds_read_b128 v[90:93], v173 offset:4096
	ds_read_b128 v[94:97], v173 offset:2048
	ds_read_b128 v[108:111], v172
	v_mfma_f32_16x16x32_bf16 v[2:5], v[174:177], v[82:85], v[2:5]
	s_waitcnt lgkmcnt(0)
	v_mfma_f32_16x16x32_bf16 v[38:41], v[78:81], v[94:97], v[38:41]
	v_add_u32_e32 v82, v114, v119
	v_add_u32_e32 v172, v118, v119
	v_mfma_f32_16x16x32_bf16 v[54:57], v[74:77], v[94:97], v[54:57]
	v_mfma_f32_16x16x32_bf16 v[58:61], v[66:69], v[94:97], v[58:61]
	v_mfma_f32_16x16x32_bf16 v[26:29], v[62:65], v[94:97], v[26:29]
	v_add_u32_e32 v94, v117, v119
	v_mfma_f32_16x16x32_bf16 v[50:53], v[78:81], v[90:93], v[50:53]
	v_mfma_f32_16x16x32_bf16 v[46:49], v[74:77], v[90:93], v[46:49]
	v_mfma_f32_16x16x32_bf16 v[42:45], v[66:69], v[90:93], v[42:45]
	v_mfma_f32_16x16x32_bf16 v[14:17], v[62:65], v[90:93], v[14:17]
	v_add_u32_e32 v90, v116, v119
	v_mfma_f32_16x16x32_bf16 v[6:9], v[78:81], v[108:111], v[6:9]
	v_mfma_f32_16x16x32_bf16 v[34:37], v[74:77], v[108:111], v[34:37]
	v_mfma_f32_16x16x32_bf16 v[70:73], v[66:69], v[108:111], v[70:73]
	v_mfma_f32_16x16x32_bf16 v[30:33], v[62:65], v[108:111], v[30:33]
	v_mfma_f32_16x16x32_bf16 v[78:81], v[78:81], v[86:89], v[22:25]
	s_nop 2
	ds_read_b128 v[22:25], v82
	ds_read_b128 v[82:85], v90 offset:2048
	v_mfma_f32_16x16x32_bf16 v[74:77], v[74:77], v[86:89], v[18:21]
	s_nop 2
	ds_read_b128 v[18:21], v90 offset:4096
	ds_read_b128 v[90:93], v90 offset:6144
	v_mfma_f32_16x16x32_bf16 v[66:69], v[66:69], v[86:89], v[10:13]
	s_nop 2
	ds_read_b128 v[10:13], v94 offset:32768
	ds_read_b128 v[94:97], v172 offset:34816
	ds_read_b128 v[108:111], v172 offset:36864
	ds_read_b128 v[172:175], v172 offset:38912
	v_mfma_f32_16x16x32_bf16 v[2:5], v[62:65], v[86:89], v[2:5]
	s_waitcnt vmcnt(0)
	s_waitcnt lgkmcnt(0)
	v_mfma_f32_16x16x32_bf16 v[2:5], v[172:175], v[90:93], v[2:5]
	s_waitcnt lgkmcnt(0)
	s_barrier
	v_mfma_f32_16x16x32_bf16 v[62:65], v[10:13], v[22:25], v[6:9]
	v_mfma_f32_16x16x32_bf16 v[86:89], v[94:97], v[22:25], v[34:37]
	v_mfma_f32_16x16x32_bf16 v[70:73], v[108:111], v[22:25], v[70:73]
	v_mfma_f32_16x16x32_bf16 v[176:179], v[172:175], v[22:25], v[30:33]
	v_mfma_f32_16x16x32_bf16 v[202:205], v[10:13], v[82:85], v[38:41]
	v_mfma_f32_16x16x32_bf16 v[54:57], v[94:97], v[82:85], v[54:57]
	v_mfma_f32_16x16x32_bf16 v[58:61], v[108:111], v[82:85], v[58:61]
	v_mfma_f32_16x16x32_bf16 v[34:37], v[172:175], v[82:85], v[26:29]
	v_mfma_f32_16x16x32_bf16 v[30:33], v[10:13], v[18:21], v[50:53]
	v_mfma_f32_16x16x32_bf16 v[26:29], v[94:97], v[18:21], v[46:49]
	v_mfma_f32_16x16x32_bf16 v[22:25], v[108:111], v[18:21], v[42:45]
	v_mfma_f32_16x16x32_bf16 v[18:21], v[172:175], v[18:21], v[14:17]
	v_mfma_f32_16x16x32_bf16 v[14:17], v[10:13], v[90:93], v[78:81]
	v_mfma_f32_16x16x32_bf16 v[10:13], v[94:97], v[90:93], v[74:77]
	v_mfma_f32_16x16x32_bf16 v[6:9], v[108:111], v[90:93], v[66:69]
	s_mul_hi_i32 s54, s70, 0x2aaaaaab
	s_lshr_b32 s55, s54, 31
	s_ashr_i32 s54, s54, 2
	s_add_i32 s13, s54, s55
	s_mul_i32 s54, s13, 24
	s_sub_i32 s14, s70, s54
	v_readfirstlane_b32 s54, v137
	s_lshr_b32 s54, s54, 6
	s_and_b32 s19, s54, 1
	s_lshr_b32 s54, s54, 1
	s_lshl_b32 s54, s54, 6
	s_lshl_b32 s50, s14, 8
	s_add_i32 s50, s50, s54
	s_lshl_b32 s51, s13, 7
	s_lshl_b32 s54, s19, 6
	s_add_i32 s51, s51, s54
	s_add_i32 s54, s50, 0xfffff000
	s_ashr_i32 s54, s54, 10
	s_add_i32 s54, s54, 1
	s_cmpk_lt_i32 s50, 0x1000
	s_cselect_b32 s52, 0, s54
	v_readlane_b32 s53, v255, 40
	v_and_b32_e32 v250, 63, v137
	v_and_b32_e32 v251, 15, v250
	v_lshrrev_b32_e32 v252, 4, v250
	s_mul_i32 s54, s53, 3
	s_add_i32 s54, s54, s52
	s_mul_i32 s54, s54, 0x6000
	s_add_u32 s22, s94, 0x6300000
	s_addc_u32 s23, s95, 0
	s_add_u32 s22, s22, s54
	s_addc_u32 s23, s23, 0
	s_add_u32 s26, s94, 0x6348000
	s_addc_u32 s27, s95, 0
	v_add_u32_e32 v242, s50, v251
	v_lshlrev_b32_e32 v242, 12, v242
	s_lshl_b32 s54, s51, 2
	v_lshl_add_u32 v242, v252, 4, v242
	v_add_u32_e32 v242, s54, v242
	s_add_i32 s55, s51, 5120
	s_lshl_b32 s55, s55, 2
	v_lshl_add_u32 v246, v252, 4, s55
	v_add_u32_e32 v243, 0x10000, v242
	v_add_u32_e32 v244, 0x20000, v242
	v_add_u32_e32 v245, 0x30000, v242
	global_load_dwordx4 v[226:229], v246, s[22:23]
	global_load_dwordx4 v[230:233], v246, s[22:23] offset:64
	global_load_dwordx4 v[234:237], v246, s[22:23] offset:128
	global_load_dwordx4 v[238:241], v246, s[22:23] offset:192
	global_load_dwordx4 v[38:41], v242, s[26:27]
	global_load_dwordx4 v[42:45], v242, s[26:27] offset:64
	global_load_dwordx4 v[46:49], v242, s[26:27] offset:128
	global_load_dwordx4 v[50:53], v242, s[26:27] offset:192
	global_load_dwordx4 v[66:69], v243, s[26:27]
	global_load_dwordx4 v[74:77], v243, s[26:27] offset:64
	global_load_dwordx4 v[78:81], v243, s[26:27] offset:128
	global_load_dwordx4 v[82:85], v243, s[26:27] offset:192
	global_load_dwordx4 v[90:93], v244, s[26:27]
	global_load_dwordx4 v[94:97], v244, s[26:27] offset:64
	global_load_dwordx4 v[108:111], v244, s[26:27] offset:128
	global_load_dwordx4 v[172:175], v244, s[26:27] offset:192
	global_load_dwordx4 v[206:209], v245, s[26:27]
	global_load_dwordx4 v[210:213], v245, s[26:27] offset:64
	global_load_dwordx4 v[214:217], v245, s[26:27] offset:128
	global_load_dwordx4 v[218:221], v245, s[26:27] offset:192
	v_mov_b32_e32 v248, 0x3fd744fd
	v_mov_b32_e32 v249, 0x3fd744fd
	s_waitcnt vmcnt(12)
	v_pk_mul_f32 v[38:39], v[38:39], v[248:249]
	v_pk_mul_f32 v[40:41], v[40:41], v[248:249]
	v_pk_fma_f32 v[62:63], v[62:63], v[226:227], v[38:39]
	v_pk_fma_f32 v[64:65], v[64:65], v[228:229], v[40:41]
	v_pk_mul_f32 v[42:43], v[42:43], v[248:249]
	v_pk_mul_f32 v[44:45], v[44:45], v[248:249]
	v_pk_fma_f32 v[86:87], v[86:87], v[230:231], v[42:43]
	v_pk_fma_f32 v[88:89], v[88:89], v[232:233], v[44:45]
	v_pk_mul_f32 v[46:47], v[46:47], v[248:249]
	v_pk_mul_f32 v[48:49], v[48:49], v[248:249]
	v_pk_fma_f32 v[70:71], v[70:71], v[234:235], v[46:47]
	v_pk_fma_f32 v[72:73], v[72:73], v[236:237], v[48:49]
	v_pk_mul_f32 v[50:51], v[50:51], v[248:249]
	v_pk_mul_f32 v[52:53], v[52:53], v[248:249]
	v_pk_fma_f32 v[176:177], v[176:177], v[238:239], v[50:51]
	v_pk_fma_f32 v[178:179], v[178:179], v[240:241], v[52:53]
	s_waitcnt vmcnt(8)
	v_pk_mul_f32 v[66:67], v[66:67], v[248:249]
	v_pk_mul_f32 v[68:69], v[68:69], v[248:249]
	v_pk_fma_f32 v[202:203], v[202:203], v[226:227], v[66:67]
	v_pk_fma_f32 v[204:205], v[204:205], v[228:229], v[68:69]
	v_pk_mul_f32 v[74:75], v[74:75], v[248:249]
	v_pk_mul_f32 v[76:77], v[76:77], v[248:249]
	v_pk_fma_f32 v[54:55], v[54:55], v[230:231], v[74:75]
	v_pk_fma_f32 v[56:57], v[56:57], v[232:233], v[76:77]
	v_pk_mul_f32 v[78:79], v[78:79], v[248:249]
	v_pk_mul_f32 v[80:81], v[80:81], v[248:249]
	v_pk_fma_f32 v[58:59], v[58:59], v[234:235], v[78:79]
	v_pk_fma_f32 v[60:61], v[60:61], v[236:237], v[80:81]
	v_pk_mul_f32 v[82:83], v[82:83], v[248:249]
	v_pk_mul_f32 v[84:85], v[84:85], v[248:249]
	v_pk_fma_f32 v[34:35], v[34:35], v[238:239], v[82:83]
	v_pk_fma_f32 v[36:37], v[36:37], v[240:241], v[84:85]
	s_waitcnt vmcnt(4)
	v_pk_mul_f32 v[90:91], v[90:91], v[248:249]
	v_pk_mul_f32 v[92:93], v[92:93], v[248:249]
	v_pk_fma_f32 v[30:31], v[30:31], v[226:227], v[90:91]
	v_pk_fma_f32 v[32:33], v[32:33], v[228:229], v[92:93]
	v_pk_mul_f32 v[94:95], v[94:95], v[248:249]
	v_pk_mul_f32 v[96:97], v[96:97], v[248:249]
	v_pk_fma_f32 v[26:27], v[26:27], v[230:231], v[94:95]
	v_pk_fma_f32 v[28:29], v[28:29], v[232:233], v[96:97]
	v_pk_mul_f32 v[108:109], v[108:109], v[248:249]
	v_pk_mul_f32 v[110:111], v[110:111], v[248:249]
	v_pk_fma_f32 v[22:23], v[22:23], v[234:235], v[108:109]
	v_pk_fma_f32 v[24:25], v[24:25], v[236:237], v[110:111]
	v_pk_mul_f32 v[172:173], v[172:173], v[248:249]
	v_pk_mul_f32 v[174:175], v[174:175], v[248:249]
	v_pk_fma_f32 v[18:19], v[18:19], v[238:239], v[172:173]
	v_pk_fma_f32 v[20:21], v[20:21], v[240:241], v[174:175]
	s_waitcnt vmcnt(0)
	v_pk_mul_f32 v[206:207], v[206:207], v[248:249]
	v_pk_mul_f32 v[208:209], v[208:209], v[248:249]
	v_pk_fma_f32 v[14:15], v[14:15], v[226:227], v[206:207]
	v_pk_fma_f32 v[16:17], v[16:17], v[228:229], v[208:209]
	v_pk_mul_f32 v[210:211], v[210:211], v[248:249]
	v_pk_mul_f32 v[212:213], v[212:213], v[248:249]
	v_pk_fma_f32 v[10:11], v[10:11], v[230:231], v[210:211]
	v_pk_fma_f32 v[12:13], v[12:13], v[232:233], v[212:213]
	v_pk_mul_f32 v[214:215], v[214:215], v[248:249]
	v_pk_mul_f32 v[216:217], v[216:217], v[248:249]
	v_pk_fma_f32 v[6:7], v[6:7], v[234:235], v[214:215]
	v_pk_fma_f32 v[8:9], v[8:9], v[236:237], v[216:217]
	v_pk_mul_f32 v[218:219], v[218:219], v[248:249]
	v_pk_mul_f32 v[220:221], v[220:221], v[248:249]
	v_pk_fma_f32 v[2:3], v[2:3], v[238:239], v[218:219]
	v_pk_fma_f32 v[4:5], v[4:5], v[240:241], v[220:221]
	v_pk_mul_f32 v[208:209], v[62:63], v[62:63]
	v_pk_add_f32 v[206:207], v[62:63], v[64:65]
	v_pk_fma_f32 v[208:209], v[64:65], v[64:65], v[208:209]
	v_pk_add_f32 v[206:207], v[206:207], v[86:87]
	v_pk_fma_f32 v[208:209], v[86:87], v[86:87], v[208:209]
	v_pk_add_f32 v[206:207], v[206:207], v[88:89]
	v_pk_fma_f32 v[208:209], v[88:89], v[88:89], v[208:209]
	v_pk_add_f32 v[206:207], v[206:207], v[70:71]
	v_pk_fma_f32 v[208:209], v[70:71], v[70:71], v[208:209]
	v_pk_add_f32 v[206:207], v[206:207], v[72:73]
	v_pk_fma_f32 v[208:209], v[72:73], v[72:73], v[208:209]
	v_pk_add_f32 v[206:207], v[206:207], v[176:177]
	v_pk_fma_f32 v[208:209], v[176:177], v[176:177], v[208:209]
	v_pk_add_f32 v[206:207], v[206:207], v[178:179]
	v_pk_fma_f32 v[208:209], v[178:179], v[178:179], v[208:209]
	v_add_f32_e32 v206, v206, v207
	v_add_f32_e32 v208, v208, v209
	v_pk_mul_f32 v[212:213], v[202:203], v[202:203]
	v_pk_add_f32 v[210:211], v[202:203], v[204:205]
	v_pk_fma_f32 v[212:213], v[204:205], v[204:205], v[212:213]
	v_pk_add_f32 v[210:211], v[210:211], v[54:55]
	v_pk_fma_f32 v[212:213], v[54:55], v[54:55], v[212:213]
	v_pk_add_f32 v[210:211], v[210:211], v[56:57]
	v_pk_fma_f32 v[212:213], v[56:57], v[56:57], v[212:213]
	v_pk_add_f32 v[210:211], v[210:211], v[58:59]
	v_pk_fma_f32 v[212:213], v[58:59], v[58:59], v[212:213]
	v_pk_add_f32 v[210:211], v[210:211], v[60:61]
	v_pk_fma_f32 v[212:213], v[60:61], v[60:61], v[212:213]
	v_pk_add_f32 v[210:211], v[210:211], v[34:35]
	v_pk_fma_f32 v[212:213], v[34:35], v[34:35], v[212:213]
	v_pk_add_f32 v[210:211], v[210:211], v[36:37]
	v_pk_fma_f32 v[212:213], v[36:37], v[36:37], v[212:213]
	v_add_f32_e32 v210, v210, v211
	v_add_f32_e32 v212, v212, v213
	v_pk_mul_f32 v[216:217], v[30:31], v[30:31]
	v_pk_add_f32 v[214:215], v[30:31], v[32:33]
	v_pk_fma_f32 v[216:217], v[32:33], v[32:33], v[216:217]
	v_pk_add_f32 v[214:215], v[214:215], v[26:27]
	v_pk_fma_f32 v[216:217], v[26:27], v[26:27], v[216:217]
	v_pk_add_f32 v[214:215], v[214:215], v[28:29]
	v_pk_fma_f32 v[216:217], v[28:29], v[28:29], v[216:217]
	v_pk_add_f32 v[214:215], v[214:215], v[22:23]
	v_pk_fma_f32 v[216:217], v[22:23], v[22:23], v[216:217]
	v_pk_add_f32 v[214:215], v[214:215], v[24:25]
	v_pk_fma_f32 v[216:217], v[24:25], v[24:25], v[216:217]
	v_pk_add_f32 v[214:215], v[214:215], v[18:19]
	v_pk_fma_f32 v[216:217], v[18:19], v[18:19], v[216:217]
	v_pk_add_f32 v[214:215], v[214:215], v[20:21]
	v_pk_fma_f32 v[216:217], v[20:21], v[20:21], v[216:217]
	v_add_f32_e32 v214, v214, v215
	v_add_f32_e32 v216, v216, v217
	v_pk_mul_f32 v[220:221], v[14:15], v[14:15]
	v_pk_add_f32 v[218:219], v[14:15], v[16:17]
	v_pk_fma_f32 v[220:221], v[16:17], v[16:17], v[220:221]
	v_pk_add_f32 v[218:219], v[218:219], v[10:11]
	v_pk_fma_f32 v[220:221], v[10:11], v[10:11], v[220:221]
	v_pk_add_f32 v[218:219], v[218:219], v[12:13]
	v_pk_fma_f32 v[220:221], v[12:13], v[12:13], v[220:221]
	v_pk_add_f32 v[218:219], v[218:219], v[6:7]
	v_pk_fma_f32 v[220:221], v[6:7], v[6:7], v[220:221]
	v_pk_add_f32 v[218:219], v[218:219], v[8:9]
	v_pk_fma_f32 v[220:221], v[8:9], v[8:9], v[220:221]
	v_pk_add_f32 v[218:219], v[218:219], v[2:3]
	v_pk_fma_f32 v[220:221], v[2:3], v[2:3], v[220:221]
	v_pk_add_f32 v[218:219], v[218:219], v[4:5]
	v_pk_fma_f32 v[220:221], v[4:5], v[4:5], v[220:221]
	v_add_f32_e32 v218, v218, v219
	v_add_f32_e32 v220, v220, v221
	s_nop 1
	v_permlane16_swap_b32_e32 v206, v210
	v_permlane16_swap_b32_e32 v214, v218
	v_permlane16_swap_b32_e32 v208, v212
	v_permlane16_swap_b32_e32 v216, v220
	v_add_f32_e32 v206, v206, v210
	v_add_f32_e32 v214, v214, v218
	v_add_f32_e32 v208, v208, v212
	v_add_f32_e32 v216, v216, v220
	s_nop 1
	v_permlane32_swap_b32_e32 v206, v214
	v_permlane32_swap_b32_e32 v208, v216
	v_add_f32_e32 v248, v206, v214
	v_add_f32_e32 v249, v208, v216
	s_add_u32 s34, s94, 0x11e5e100
	s_addc_u32 s35, s95, 0
	v_add_u32_e32 v247, s50, v250
	v_lshlrev_b32_e32 v247, 7, v247
	s_lshl_b32 s54, s13, 4
	s_lshl_b32 s55, s19, 3
	s_add_i32 s54, s54, s55
	v_add_u32_e32 v246, s54, v247
	global_store_dwordx2 v246, v[248:249], s[34:35] sc1
	v_readlane_b32 s36, v253, 15
	v_readlane_b32 s37, v253, 16
	v_readlane_b32 s48, v253, 17
	v_readlane_b32 s49, v253, 18
	s_lshl_b32 s54, s53, 10
	s_add_i32 s54, s54, s51
	s_lshl_b32 s54, s54, 2
	v_lshl_add_u32 v222, v252, 4, s54
	s_nop 3
	global_load_dwordx4 v[66:69], v222, s[36:37]
	global_load_dwordx4 v[74:77], v222, s[36:37] offset:64
	global_load_dwordx4 v[78:81], v222, s[36:37] offset:128
	global_load_dwordx4 v[82:85], v222, s[36:37] offset:192
	global_load_dwordx4 v[90:93], v222, s[48:49]
	global_load_dwordx4 v[94:97], v222, s[48:49] offset:64
	global_load_dwordx4 v[108:111], v222, s[48:49] offset:128
	global_load_dwordx4 v[172:175], v222, s[48:49] offset:192
	s_waitcnt vmcnt(8)
	s_barrier
	v_cmp_eq_u32_e64 s[36:37], 0, v137
	s_nop 3
	s_and_saveexec_b64 s[48:49], s[36:37]
	s_cbranch_execz .Lln2_xdone
	s_mul_i32 s54, s53, 384
	s_lshl_b32 s55, s14, 2
	s_add_i32 s54, s54, s55
	s_add_i32 s54, s54, 192
	s_add_u32 s36, s94, 0x11e5d700
	s_addc_u32 s37, s95, 0
	s_add_u32 s36, s36, s54
	s_addc_u32 s37, s37, 0
	v_mov_b32_e32 v248, 1
	s_mov_b32 s55, 0x100000
	global_atomic_add v1, v248, s[36:37]
.Lln2_poll:
	global_load_dword v248, v1, s[36:37] sc1
	s_waitcnt vmcnt(0)
	v_cmp_lt_u32_e32 vcc, 7, v248
	s_cbranch_vccnz .Lln2_xdone
	s_sleep 1
	s_add_i32 s55, s55, -1
	s_cmp_lg_u32 s55, 0
	s_cbranch_scc1 .Lln2_poll
.Lln2_xdone:
	s_or_b64 exec, exec, s[48:49]
	s_barrier
	global_load_dwordx4 v[226:229], v247, s[34:35] sc1
	global_load_dwordx4 v[230:233], v247, s[34:35] offset:16 sc1
	global_load_dwordx4 v[234:237], v247, s[34:35] offset:32 sc1
	global_load_dwordx4 v[238:241], v247, s[34:35] offset:48 sc1
	global_load_dwordx4 v[38:41], v247, s[34:35] offset:64 sc1
	global_load_dwordx4 v[42:45], v247, s[34:35] offset:80 sc1
	global_load_dwordx4 v[46:49], v247, s[34:35] offset:96 sc1
	global_load_dwordx4 v[50:53], v247, s[34:35] offset:112 sc1
	s_waitcnt vmcnt(0)
	v_add_f32_e32 v206, 0, v226
	v_add_f32_e32 v207, 0, v227
	v_add_f32_e32 v206, v206, v228
	v_add_f32_e32 v207, v207, v229
	v_add_f32_e32 v206, v206, v230
	v_add_f32_e32 v207, v207, v231
	v_add_f32_e32 v206, v206, v232
	v_add_f32_e32 v207, v207, v233
	v_add_f32_e32 v206, v206, v234
	v_add_f32_e32 v207, v207, v235
	v_add_f32_e32 v206, v206, v236
	v_add_f32_e32 v207, v207, v237
	v_add_f32_e32 v206, v206, v238
	v_add_f32_e32 v207, v207, v239
	v_add_f32_e32 v206, v206, v240
	v_add_f32_e32 v207, v207, v241
	v_add_f32_e32 v206, v206, v38
	v_add_f32_e32 v207, v207, v39
	v_add_f32_e32 v206, v206, v40
	v_add_f32_e32 v207, v207, v41
	v_add_f32_e32 v206, v206, v42
	v_add_f32_e32 v207, v207, v43
	v_add_f32_e32 v206, v206, v44
	v_add_f32_e32 v207, v207, v45
	v_add_f32_e32 v206, v206, v46
	v_add_f32_e32 v207, v207, v47
	v_add_f32_e32 v206, v206, v48
	v_add_f32_e32 v207, v207, v49
	v_add_f32_e32 v206, v206, v50
	v_add_f32_e32 v207, v207, v51
	v_add_f32_e32 v206, v206, v52
	v_add_f32_e32 v207, v207, v53
	s_add_u32 s22, s22, 0x12000
	s_addc_u32 s23, s23, 0
	s_cmp_eq_u32 s53, 3
	s_cbranch_scc1 .Lln2_nomod
	s_add_i32 s54, s51, 0
	s_lshl_b32 s54, s54, 2
	v_lshl_add_u32 v222, v252, 4, s54
	v_add_u32_e32 v246, 0x1000, v222
	global_load_dwordx4 v[226:229], v222, s[22:23]
	global_load_dwordx4 v[230:233], v222, s[22:23] offset:64
	global_load_dwordx4 v[234:237], v222, s[22:23] offset:128
	global_load_dwordx4 v[238:241], v222, s[22:23] offset:192
	global_load_dwordx4 v[38:41], v246, s[22:23]
	global_load_dwordx4 v[42:45], v246, s[22:23] offset:64
	global_load_dwordx4 v[46:49], v246, s[22:23] offset:128
	global_load_dwordx4 v[50:53], v246, s[22:23] offset:192
.Lln2_nomod:
	v_mul_f32_e32 v208, 0x3a800000, v206
	v_mul_f32_e32 v209, v208, v208
	v_mov_b32_e32 v216, 0x3a800000
	v_fma_f32 v209, v207, v216, -v209
	v_max_f32_e32 v209, 0, v209
	v_add_f32_e32 v209, 0x3727c5ac, v209
	v_rsq_f32_e32 v209, v209
	v_mov_b32_e32 v210, v208
	v_mov_b32_e32 v211, v208
	v_mov_b32_e32 v214, v209
	v_mov_b32_e32 v215, v209
	s_nop 1
	v_permlane16_swap_b32_e32 v210, v211
	v_permlane16_swap_b32_e32 v214, v215
	v_mov_b32_e32 v212, v210
	v_mov_b32_e32 v213, v211
	v_mov_b32_e32 v216, v214
	v_mov_b32_e32 v217, v215
	s_nop 1
	v_permlane32_swap_b32_e32 v210, v212
	v_permlane32_swap_b32_e32 v211, v213
	v_permlane32_swap_b32_e32 v214, v216
	v_permlane32_swap_b32_e32 v215, v217
	s_cmp_eq_u32 s53, 3
	s_cselect_b32 s26, s92, s26
	s_cselect_b32 s27, s93, s27
	v_sub_f32_e32 v62, v62, v210
	v_sub_f32_e32 v63, v63, v210
	v_sub_f32_e32 v64, v64, v210
	v_sub_f32_e32 v65, v65, v210
	v_mul_f32_e32 v62, v214, v62
	v_mul_f32_e32 v63, v214, v63
	v_mul_f32_e32 v64, v214, v64
	v_mul_f32_e32 v65, v214, v65
	v_fma_f32 v62, v66, v62, v90
	v_fma_f32 v63, v67, v63, v91
	v_fma_f32 v64, v68, v64, v92
	v_fma_f32 v65, v69, v65, v93
	global_store_dwordx4 v242, v[62:65], s[26:27]
	v_sub_f32_e32 v86, v86, v210
	v_sub_f32_e32 v87, v87, v210
	v_sub_f32_e32 v88, v88, v210
	v_sub_f32_e32 v89, v89, v210
	v_mul_f32_e32 v86, v214, v86
	v_mul_f32_e32 v87, v214, v87
	v_mul_f32_e32 v88, v214, v88
	v_mul_f32_e32 v89, v214, v89
	v_fma_f32 v86, v74, v86, v94
	v_fma_f32 v87, v75, v87, v95
	v_fma_f32 v88, v76, v88, v96
	v_fma_f32 v89, v77, v89, v97
	global_store_dwordx4 v242, v[86:89], s[26:27] offset:64
	v_sub_f32_e32 v70, v70, v210
	v_sub_f32_e32 v71, v71, v210
	v_sub_f32_e32 v72, v72, v210
	v_sub_f32_e32 v73, v73, v210
	v_mul_f32_e32 v70, v214, v70
	v_mul_f32_e32 v71, v214, v71
	v_mul_f32_e32 v72, v214, v72
	v_mul_f32_e32 v73, v214, v73
	v_fma_f32 v70, v78, v70, v108
	v_fma_f32 v71, v79, v71, v109
	v_fma_f32 v72, v80, v72, v110
	v_fma_f32 v73, v81, v73, v111
	global_store_dwordx4 v242, v[70:73], s[26:27] offset:128
	v_sub_f32_e32 v176, v176, v210
	v_sub_f32_e32 v177, v177, v210
	v_sub_f32_e32 v178, v178, v210
	v_sub_f32_e32 v179, v179, v210
	v_mul_f32_e32 v176, v214, v176
	v_mul_f32_e32 v177, v214, v177
	v_mul_f32_e32 v178, v214, v178
	v_mul_f32_e32 v179, v214, v179
	v_fma_f32 v176, v82, v176, v172
	v_fma_f32 v177, v83, v177, v173
	v_fma_f32 v178, v84, v178, v174
	v_fma_f32 v179, v85, v179, v175
	global_store_dwordx4 v242, v[176:179], s[26:27] offset:192
	v_sub_f32_e32 v202, v202, v211
	v_sub_f32_e32 v203, v203, v211
	v_sub_f32_e32 v204, v204, v211
	v_sub_f32_e32 v205, v205, v211
	v_mul_f32_e32 v202, v215, v202
	v_mul_f32_e32 v203, v215, v203
	v_mul_f32_e32 v204, v215, v204
	v_mul_f32_e32 v205, v215, v205
	v_fma_f32 v202, v66, v202, v90
	v_fma_f32 v203, v67, v203, v91
	v_fma_f32 v204, v68, v204, v92
	v_fma_f32 v205, v69, v205, v93
	global_store_dwordx4 v243, v[202:205], s[26:27]
	v_sub_f32_e32 v54, v54, v211
	v_sub_f32_e32 v55, v55, v211
	v_sub_f32_e32 v56, v56, v211
	v_sub_f32_e32 v57, v57, v211
	v_mul_f32_e32 v54, v215, v54
	v_mul_f32_e32 v55, v215, v55
	v_mul_f32_e32 v56, v215, v56
	v_mul_f32_e32 v57, v215, v57
	v_fma_f32 v54, v74, v54, v94
	v_fma_f32 v55, v75, v55, v95
	v_fma_f32 v56, v76, v56, v96
	v_fma_f32 v57, v77, v57, v97
	global_store_dwordx4 v243, v[54:57], s[26:27] offset:64
	v_sub_f32_e32 v58, v58, v211
	v_sub_f32_e32 v59, v59, v211
	v_sub_f32_e32 v60, v60, v211
	v_sub_f32_e32 v61, v61, v211
	v_mul_f32_e32 v58, v215, v58
	v_mul_f32_e32 v59, v215, v59
	v_mul_f32_e32 v60, v215, v60
	v_mul_f32_e32 v61, v215, v61
	v_fma_f32 v58, v78, v58, v108
	v_fma_f32 v59, v79, v59, v109
	v_fma_f32 v60, v80, v60, v110
	v_fma_f32 v61, v81, v61, v111
	global_store_dwordx4 v243, v[58:61], s[26:27] offset:128
	v_sub_f32_e32 v34, v34, v211
	v_sub_f32_e32 v35, v35, v211
	v_sub_f32_e32 v36, v36, v211
	v_sub_f32_e32 v37, v37, v211
	v_mul_f32_e32 v34, v215, v34
	v_mul_f32_e32 v35, v215, v35
	v_mul_f32_e32 v36, v215, v36
	v_mul_f32_e32 v37, v215, v37
	v_fma_f32 v34, v82, v34, v172
	v_fma_f32 v35, v83, v35, v173
	v_fma_f32 v36, v84, v36, v174
	v_fma_f32 v37, v85, v37, v175
	global_store_dwordx4 v243, v[34:37], s[26:27] offset:192
	v_sub_f32_e32 v30, v30, v212
	v_sub_f32_e32 v31, v31, v212
	v_sub_f32_e32 v32, v32, v212
	v_sub_f32_e32 v33, v33, v212
	v_mul_f32_e32 v30, v216, v30
	v_mul_f32_e32 v31, v216, v31
	v_mul_f32_e32 v32, v216, v32
	v_mul_f32_e32 v33, v216, v33
	v_fma_f32 v30, v66, v30, v90
	v_fma_f32 v31, v67, v31, v91
	v_fma_f32 v32, v68, v32, v92
	v_fma_f32 v33, v69, v33, v93
	global_store_dwordx4 v244, v[30:33], s[26:27]
	v_sub_f32_e32 v26, v26, v212
	v_sub_f32_e32 v27, v27, v212
	v_sub_f32_e32 v28, v28, v212
	v_sub_f32_e32 v29, v29, v212
	v_mul_f32_e32 v26, v216, v26
	v_mul_f32_e32 v27, v216, v27
	v_mul_f32_e32 v28, v216, v28
	v_mul_f32_e32 v29, v216, v29
	v_fma_f32 v26, v74, v26, v94
	v_fma_f32 v27, v75, v27, v95
	v_fma_f32 v28, v76, v28, v96
	v_fma_f32 v29, v77, v29, v97
	global_store_dwordx4 v244, v[26:29], s[26:27] offset:64
	v_sub_f32_e32 v22, v22, v212
	v_sub_f32_e32 v23, v23, v212
	v_sub_f32_e32 v24, v24, v212
	v_sub_f32_e32 v25, v25, v212
	v_mul_f32_e32 v22, v216, v22
	v_mul_f32_e32 v23, v216, v23
	v_mul_f32_e32 v24, v216, v24
	v_mul_f32_e32 v25, v216, v25
	v_fma_f32 v22, v78, v22, v108
	v_fma_f32 v23, v79, v23, v109
	v_fma_f32 v24, v80, v24, v110
	v_fma_f32 v25, v81, v25, v111
	global_store_dwordx4 v244, v[22:25], s[26:27] offset:128
	v_sub_f32_e32 v18, v18, v212
	v_sub_f32_e32 v19, v19, v212
	v_sub_f32_e32 v20, v20, v212
	v_sub_f32_e32 v21, v21, v212
	v_mul_f32_e32 v18, v216, v18
	v_mul_f32_e32 v19, v216, v19
	v_mul_f32_e32 v20, v216, v20
	v_mul_f32_e32 v21, v216, v21
	v_fma_f32 v18, v82, v18, v172
	v_fma_f32 v19, v83, v19, v173
	v_fma_f32 v20, v84, v20, v174
	v_fma_f32 v21, v85, v21, v175
	global_store_dwordx4 v244, v[18:21], s[26:27] offset:192
	v_sub_f32_e32 v14, v14, v213
	v_sub_f32_e32 v15, v15, v213
	v_sub_f32_e32 v16, v16, v213
	v_sub_f32_e32 v17, v17, v213
	v_mul_f32_e32 v14, v217, v14
	v_mul_f32_e32 v15, v217, v15
	v_mul_f32_e32 v16, v217, v16
	v_mul_f32_e32 v17, v217, v17
	v_fma_f32 v14, v66, v14, v90
	v_fma_f32 v15, v67, v15, v91
	v_fma_f32 v16, v68, v16, v92
	v_fma_f32 v17, v69, v17, v93
	global_store_dwordx4 v245, v[14:17], s[26:27]
	v_sub_f32_e32 v10, v10, v213
	v_sub_f32_e32 v11, v11, v213
	v_sub_f32_e32 v12, v12, v213
	v_sub_f32_e32 v13, v13, v213
	v_mul_f32_e32 v10, v217, v10
	v_mul_f32_e32 v11, v217, v11
	v_mul_f32_e32 v12, v217, v12
	v_mul_f32_e32 v13, v217, v13
	v_fma_f32 v10, v74, v10, v94
	v_fma_f32 v11, v75, v11, v95
	v_fma_f32 v12, v76, v12, v96
	v_fma_f32 v13, v77, v13, v97
	global_store_dwordx4 v245, v[10:13], s[26:27] offset:64
	v_sub_f32_e32 v6, v6, v213
	v_sub_f32_e32 v7, v7, v213
	v_sub_f32_e32 v8, v8, v213
	v_sub_f32_e32 v9, v9, v213
	v_mul_f32_e32 v6, v217, v6
	v_mul_f32_e32 v7, v217, v7
	v_mul_f32_e32 v8, v217, v8
	v_mul_f32_e32 v9, v217, v9
	v_fma_f32 v6, v78, v6, v108
	v_fma_f32 v7, v79, v7, v109
	v_fma_f32 v8, v80, v8, v110
	v_fma_f32 v9, v81, v9, v111
	global_store_dwordx4 v245, v[6:9], s[26:27] offset:128
	v_sub_f32_e32 v2, v2, v213
	v_sub_f32_e32 v3, v3, v213
	v_sub_f32_e32 v4, v4, v213
	v_sub_f32_e32 v5, v5, v213
	v_mul_f32_e32 v2, v217, v2
	v_mul_f32_e32 v3, v217, v3
	v_mul_f32_e32 v4, v217, v4
	v_mul_f32_e32 v5, v217, v5
	v_fma_f32 v2, v82, v2, v172
	v_fma_f32 v3, v83, v3, v173
	v_fma_f32 v4, v84, v4, v174
	v_fma_f32 v5, v85, v5, v175
	global_store_dwordx4 v245, v[2:5], s[26:27] offset:192
	s_cmp_eq_u32 s53, 3
	s_cbranch_scc1 .Lln2_end
	s_add_u32 s34, s94, 0x7b48000
	s_addc_u32 s35, s95, 0
	s_waitcnt vmcnt(16)
	v_add_f32_e32 v38, 1.0, v38
	v_add_f32_e32 v39, 1.0, v39
	v_add_f32_e32 v40, 1.0, v40
	v_add_f32_e32 v41, 1.0, v41
	v_add_f32_e32 v42, 1.0, v42
	v_add_f32_e32 v43, 1.0, v43
	v_add_f32_e32 v44, 1.0, v44
	v_add_f32_e32 v45, 1.0, v45
	v_add_f32_e32 v46, 1.0, v46
	v_add_f32_e32 v47, 1.0, v47
	v_add_f32_e32 v48, 1.0, v48
	v_add_f32_e32 v49, 1.0, v49
	v_add_f32_e32 v50, 1.0, v50
	v_add_f32_e32 v51, 1.0, v51
	v_add_f32_e32 v52, 1.0, v52
	v_add_f32_e32 v53, 1.0, v53
	v_lshrrev_b32_e32 v218, 1, v242
	v_lshrrev_b32_e32 v219, 1, v243
	v_lshrrev_b32_e32 v220, 1, v244
	v_lshrrev_b32_e32 v221, 1, v245
	v_fma_f32 v62, v38, v62, v226
	v_fma_f32 v63, v39, v63, v227
	v_fma_f32 v64, v40, v64, v228
	v_fma_f32 v65, v41, v65, v229
	v_cvt_pk_bf16_f32 v62, v62, v63
	v_cvt_pk_bf16_f32 v63, v64, v65
	global_store_dwordx2 v218, v[62:63], s[34:35]
	v_fma_f32 v86, v42, v86, v230
	v_fma_f32 v87, v43, v87, v231
	v_fma_f32 v88, v44, v88, v232
	v_fma_f32 v89, v45, v89, v233
	v_cvt_pk_bf16_f32 v86, v86, v87
	v_cvt_pk_bf16_f32 v87, v88, v89
	global_store_dwordx2 v218, v[86:87], s[34:35] offset:32
	v_fma_f32 v70, v46, v70, v234
	v_fma_f32 v71, v47, v71, v235
	v_fma_f32 v72, v48, v72, v236
	v_fma_f32 v73, v49, v73, v237
	v_cvt_pk_bf16_f32 v70, v70, v71
	v_cvt_pk_bf16_f32 v71, v72, v73
	global_store_dwordx2 v218, v[70:71], s[34:35] offset:64
	v_fma_f32 v176, v50, v176, v238
	v_fma_f32 v177, v51, v177, v239
	v_fma_f32 v178, v52, v178, v240
	v_fma_f32 v179, v53, v179, v241
	v_cvt_pk_bf16_f32 v176, v176, v177
	v_cvt_pk_bf16_f32 v177, v178, v179
	global_store_dwordx2 v218, v[176:177], s[34:35] offset:96
	v_fma_f32 v202, v38, v202, v226
	v_fma_f32 v203, v39, v203, v227
	v_fma_f32 v204, v40, v204, v228
	v_fma_f32 v205, v41, v205, v229
	v_cvt_pk_bf16_f32 v202, v202, v203
	v_cvt_pk_bf16_f32 v203, v204, v205
	global_store_dwordx2 v219, v[202:203], s[34:35]
	v_fma_f32 v54, v42, v54, v230
	v_fma_f32 v55, v43, v55, v231
	v_fma_f32 v56, v44, v56, v232
	v_fma_f32 v57, v45, v57, v233
	v_cvt_pk_bf16_f32 v54, v54, v55
	v_cvt_pk_bf16_f32 v55, v56, v57
	global_store_dwordx2 v219, v[54:55], s[34:35] offset:32
	v_fma_f32 v58, v46, v58, v234
	v_fma_f32 v59, v47, v59, v235
	v_fma_f32 v60, v48, v60, v236
	v_fma_f32 v61, v49, v61, v237
	v_cvt_pk_bf16_f32 v58, v58, v59
	v_cvt_pk_bf16_f32 v59, v60, v61
	global_store_dwordx2 v219, v[58:59], s[34:35] offset:64
	v_fma_f32 v34, v50, v34, v238
	v_fma_f32 v35, v51, v35, v239
	v_fma_f32 v36, v52, v36, v240
	v_fma_f32 v37, v53, v37, v241
	v_cvt_pk_bf16_f32 v34, v34, v35
	v_cvt_pk_bf16_f32 v35, v36, v37
	global_store_dwordx2 v219, v[34:35], s[34:35] offset:96
	v_fma_f32 v30, v38, v30, v226
	v_fma_f32 v31, v39, v31, v227
	v_fma_f32 v32, v40, v32, v228
	v_fma_f32 v33, v41, v33, v229
	v_cvt_pk_bf16_f32 v30, v30, v31
	v_cvt_pk_bf16_f32 v31, v32, v33
	global_store_dwordx2 v220, v[30:31], s[34:35]
	v_fma_f32 v26, v42, v26, v230
	v_fma_f32 v27, v43, v27, v231
	v_fma_f32 v28, v44, v28, v232
	v_fma_f32 v29, v45, v29, v233
	v_cvt_pk_bf16_f32 v26, v26, v27
	v_cvt_pk_bf16_f32 v27, v28, v29
	global_store_dwordx2 v220, v[26:27], s[34:35] offset:32
	v_fma_f32 v22, v46, v22, v234
	v_fma_f32 v23, v47, v23, v235
	v_fma_f32 v24, v48, v24, v236
	v_fma_f32 v25, v49, v25, v237
	v_cvt_pk_bf16_f32 v22, v22, v23
	v_cvt_pk_bf16_f32 v23, v24, v25
	global_store_dwordx2 v220, v[22:23], s[34:35] offset:64
	v_fma_f32 v18, v50, v18, v238
	v_fma_f32 v19, v51, v19, v239
	v_fma_f32 v20, v52, v20, v240
	v_fma_f32 v21, v53, v21, v241
	v_cvt_pk_bf16_f32 v18, v18, v19
	v_cvt_pk_bf16_f32 v19, v20, v21
	global_store_dwordx2 v220, v[18:19], s[34:35] offset:96
	v_fma_f32 v14, v38, v14, v226
	v_fma_f32 v15, v39, v15, v227
	v_fma_f32 v16, v40, v16, v228
	v_fma_f32 v17, v41, v17, v229
	v_cvt_pk_bf16_f32 v14, v14, v15
	v_cvt_pk_bf16_f32 v15, v16, v17
	global_store_dwordx2 v221, v[14:15], s[34:35]
	v_fma_f32 v10, v42, v10, v230
	v_fma_f32 v11, v43, v11, v231
	v_fma_f32 v12, v44, v12, v232
	v_fma_f32 v13, v45, v13, v233
	v_cvt_pk_bf16_f32 v10, v10, v11
	v_cvt_pk_bf16_f32 v11, v12, v13
	global_store_dwordx2 v221, v[10:11], s[34:35] offset:32
	v_fma_f32 v6, v46, v6, v234
	v_fma_f32 v7, v47, v7, v235
	v_fma_f32 v8, v48, v8, v236
	v_fma_f32 v9, v49, v9, v237
	v_cvt_pk_bf16_f32 v6, v6, v7
	v_cvt_pk_bf16_f32 v7, v8, v9
	global_store_dwordx2 v221, v[6:7], s[34:35] offset:64
	v_fma_f32 v2, v50, v2, v238
	v_fma_f32 v3, v51, v3, v239
	v_fma_f32 v4, v52, v4, v240
	v_fma_f32 v5, v53, v5, v241
	v_cvt_pk_bf16_f32 v2, v2, v3
	v_cvt_pk_bf16_f32 v3, v4, v5
	global_store_dwordx2 v221, v[2:3], s[34:35] offset:96
.Lln2_end:
	s_branch .LBB0_411
.LBB0_434:
	v_readlane_b32 s8, v255, 42
	v_readlane_b32 s9, v255, 43
	s_and_b64 vcc, exec, s[8:9]
	s_cbranch_vccz .LBB0_449
	s_load_dword s6, s[78:79], 0x0
	v_readfirstlane_b32 s5, v137
	s_lshr_b32 s9, s5, 8
	v_readlane_b32 s5, v254, 40
	s_add_i32 s5, s5, s9
	s_waitcnt lgkmcnt(0)
	s_lshl_b32 s8, s6, 1
	s_add_i32 s6, s8, 0xfffffe80
	s_cmp_lt_i32 s5, 0
	s_cselect_b64 s[22:23], -1, 0
	s_cmp_gt_i32 s5, -1
	s_mov_b32 s11, s6
	s_mov_b32 s12, s5
	s_cbranch_scc1 .LBB0_437
	v_readfirstlane_b32 s11, v137
	s_lshr_b32 s11, s11, 8
	v_readlane_b32 s12, v254, 39
	s_add_i32 s12, s11, s12
	s_mov_b32 s11, s8
